# combo + HGRN2 interval 3: next-chunk decay tables: LDS reads right after the barrier, exp + table writes behind the first output MFMA
# baseline (speedup 1.0000x reference)
.LBB0_480:
	ds_read_b64_tr_b16 v[40:41], v104 offset:27648
	ds_read_b64_tr_b16 v[42:43], v104 offset:28224
	v_exp_f32_e32 v60, v118
	ds_read_b128 v[44:47], v109 offset:36864
	v_exp_f32_e32 v61, v119
	v_exp_f32_e32 v62, v120
	v_exp_f32_e32 v63, v121
	ds_read_b128 v[36:39], v108 offset:36864
	s_waitcnt lgkmcnt(1)
	v_mfma_f32_16x16x32_bf16 v[44:47], v[40:43], v[44:47], 0
	s_and_b64 vcc, exec, s[100:101]
	s_cbranch_vccz .Lefb_c3
	s_and_b64 vcc, exec, s[12:13]
	s_cbranch_vccz .Lefb_c0
	v_sub_f32_e32 v172, v173, v172
	v_mov_b32_e32 v174, 0x22800
	s_branch .Lefb_c1
.Lefb_c0:
	v_mov_b32_e32 v174, 0x22400
.Lefb_c1:
	v_exp_f32_e32 v172, v172
	v_lshl_add_u32 v174, v66, 2, v174
	s_and_b64 vcc, exec, s[8:9]
	s_cbranch_vccz .Lefb_c2
	v_sub_f32_e32 v170, v171, v170
	v_exp_f32_e32 v170, v170
	s_nop 0
	ds_write_b32 v83, v170
.Lefb_c2:
	ds_write_b32 v174, v172
.Lefb_c3:
	ds_read_b64_tr_b16 v[48:49], v104 offset:18432
	ds_read_b64_tr_b16 v[50:51], v104 offset:19008
	ds_read_b64_tr_b16 v[52:53], v104 offset:32256
	v_pk_mul_f32 v[34:35], v[34:35], v[62:63]
	v_pk_mul_f32 v[32:33], v[32:33], v[60:61]
	s_waitcnt lgkmcnt(3)
	v_mfma_f32_16x16x32_bf16 v[36:39], v[40:43], v[36:39], 0
	ds_read_b64_tr_b16 v[40:41], v106 offset:27648
	ds_read_b64_tr_b16 v[42:43], v106 offset:28224
	ds_read_b64_tr_b16 v[56:57], v107 offset:27648
	ds_read_b64_tr_b16 v[58:59], v107 offset:28224
	ds_read_b64_tr_b16 v[54:55], v104 offset:32832
	v_pk_mul_f32 v[30:31], v[30:31], v[62:63]
	v_pk_mul_f32 v[28:29], v[28:29], v[60:61]
	s_waitcnt lgkmcnt(3)
	v_mfma_f32_16x16x32_bf16 v[32:35], v[48:51], v[40:43], v[32:35]
	s_add_i32 s47, s47, 2
	s_and_b64 vcc, exec, s[60:61]
	s_mov_b32 s60, 0xffff0000
	s_waitcnt lgkmcnt(1)
	v_mfma_f32_16x16x32_bf16 v[40:43], v[48:51], v[56:59], v[28:31]
	s_nop 2
	ds_read_b128 v[28:31], v109 offset:36928
	ds_read_b64_tr_b16 v[48:49], v104 offset:23616
	ds_read_b128 v[56:59], v108 offset:36928
	s_movk_i32 s61, 0x90
	s_waitcnt lgkmcnt(2)
	v_mfma_f32_16x16x32_bf16 v[60:63], v[52:55], v[28:31], v[44:47]
	s_nop 2
	ds_read_b64_tr_b16 v[46:47], v104 offset:23040
	ds_read_b64_tr_b16 v[28:29], v106 offset:32256
	s_waitcnt lgkmcnt(2)
	v_mfma_f32_16x16x32_bf16 v[36:39], v[52:55], v[56:59], v[36:39]
	ds_read_b64_tr_b16 v[30:31], v106 offset:32832
	ds_read_b64_tr_b16 v[50:51], v107 offset:32256
	ds_read_b64_tr_b16 v[52:53], v107 offset:32832
	ds_read_b128 v[54:57], v105 offset:55296
	s_waitcnt lgkmcnt(3)
	v_mfma_f32_16x16x32_bf16 v[28:31], v[46:49], v[28:31], v[32:35]
	s_waitcnt lgkmcnt(1)
	v_mfma_f32_16x16x32_bf16 v[32:35], v[46:49], v[50:53], v[40:43]
	s_nop 2
	ds_read_b128 v[40:43], v109 offset:9216
	ds_read_b128 v[44:47], v108 offset:9216
	ds_read_b128 v[48:51], v105 offset:55360
	v_cvt_pk_bf16_f32 v52, v28, v29
	s_waitcnt lgkmcnt(1)
	v_mfma_f32_16x16x32_bf16 v[36:39], v[54:57], v[44:47], v[36:39]
	ds_read_b128 v[44:47], v109 offset:9280
	v_cvt_pk_bf16_f32 v53, v30, v31
	v_mfma_f32_16x16x32_bf16 v[40:43], v[54:57], v[40:43], v[60:63]
	s_waitcnt lgkmcnt(0)
	v_mfma_f32_16x16x32_bf16 v[40:43], v[48:51], v[44:47], v[40:43]
	ds_read_b128 v[44:47], v108 offset:9280
	ds_write_b64 v113, v[52:53] offset:46080
	s_waitcnt lgkmcnt(1)
	v_mfma_f32_16x16x32_bf16 v[36:39], v[48:51], v[44:47], v[36:39]
	v_cvt_pk_bf16_f32 v44, v32, v33
	v_cvt_pk_bf16_f32 v45, v34, v35
	ds_write_b64 v112, v[44:45] offset:46080
	v_add_u32_e32 v44, s34, v75
	v_lshl_or_b32 v180, v44, 10, v76
	v_cvt_pk_bf16_f32 v40, v40, v41
	v_cvt_pk_bf16_f32 v41, v42, v43
	v_lshl_add_u64 v[42:43], v[180:181], 1, s[92:93]
	global_store_dwordx2 v[42:43], v[40:41], off
	v_add_u32_e32 v40, s34, v77
	v_lshl_or_b32 v180, v40, 10, v76
	v_cvt_pk_bf16_f32 v36, v36, v37
	v_cvt_pk_bf16_f32 v37, v38, v39
	v_lshl_add_u64 v[38:39], v[180:181], 1, s[92:93]
	global_store_dwordx2 v[38:39], v[36:37], off
	s_waitcnt lgkmcnt(0)
	s_barrier
	s_cbranch_vccnz .LBB0_541

.LBB0_496:
	s_waitcnt lgkmcnt(0)
	s_barrier
	v_mov_b32_e32 v170, 0
	v_mov_b32_e32 v172, 0
	s_and_b64 vcc, exec, s[8:9]
	s_cbranch_vccz .Lefa_1
	s_and_b64 vcc, exec, s[30:31]
	s_cbranch_vccz .Lefa_0
	ds_read_b32 v170, v81
.Lefa_0:
	ds_read_b32 v171, v82
.Lefa_1:
	s_and_b64 vcc, exec, s[10:11]
	s_cbranch_vccz .Lefa_2
	ds_read_b32 v172, v84
.Lefa_2:
	s_and_b64 vcc, exec, s[12:13]
	s_cbranch_vccz .Lefa_3
	ds_read_b32 v173, v80 offset:16128
.Lefa_3:
	s_lshl_b32 s63, s47, 6
	s_cmp_gt_u32 s47, 3
	s_cselect_b64 s[42:43], -1, 0
	s_mov_b64 s[4:5], -1
	s_and_b64 vcc, exec, s[42:43]
	s_cbranch_vccz .LBB0_506
	s_add_i32 s48, s63, 0xffffff00
	s_sub_i32 vcc_lo, 0x10ff, s63
	s_and_b64 s[4:5], s[6:7], exec
	s_cselect_b32 s4, s48, vcc_lo
	s_add_i32 s48, s4, s76
	s_mov_b64 s[4:5], 0

.LBB0_508:
	v_add_u32_e32 v109, v72, v64
	v_add_u32_e32 v108, v73, v64
	ds_read_b64_tr_b16 v[40:41], v104 offset:27648
	ds_read_b64_tr_b16 v[42:43], v104 offset:28224
	v_exp_f32_e32 v60, v118
	v_exp_f32_e32 v61, v119
	ds_read_b128 v[44:47], v109 offset:36864
	v_exp_f32_e32 v62, v120
	v_exp_f32_e32 v63, v121
	ds_read_b128 v[36:39], v108 offset:36864
	s_waitcnt lgkmcnt(1)
	v_mfma_f32_16x16x32_bf16 v[44:47], v[40:43], v[44:47], 0
	s_and_b64 vcc, exec, s[12:13]
	s_cbranch_vccz .Lefa_c0
	v_sub_f32_e32 v172, v173, v172
	v_mov_b32_e32 v174, 0x22800
	s_branch .Lefa_c1

.Lefa_c2:
	ds_write_b32 v174, v172
	ds_read_b64_tr_b16 v[48:49], v104 offset:18432
	ds_read_b64_tr_b16 v[50:51], v104 offset:19008
	ds_read_b64_tr_b16 v[52:53], v104 offset:32256
	v_pk_mul_f32 v[30:31], v[30:31], v[62:63]
	v_pk_mul_f32 v[28:29], v[28:29], v[60:61]
	s_waitcnt lgkmcnt(3)
	v_mfma_f32_16x16x32_bf16 v[36:39], v[40:43], v[36:39], 0
	ds_read_b64_tr_b16 v[40:41], v106 offset:27648
	ds_read_b64_tr_b16 v[42:43], v106 offset:28224
	ds_read_b64_tr_b16 v[56:57], v107 offset:27648
	ds_read_b64_tr_b16 v[58:59], v107 offset:28224
	ds_read_b64_tr_b16 v[54:55], v104 offset:32832
	v_pk_mul_f32 v[34:35], v[34:35], v[62:63]
	v_pk_mul_f32 v[32:33], v[32:33], v[60:61]
	s_waitcnt lgkmcnt(3)
	v_mfma_f32_16x16x32_bf16 v[28:31], v[48:51], v[40:43], v[28:31]
	v_add_u32_e32 v113, v72, v74
	v_add_u32_e32 v112, v73, v74
	v_readlane_b32 s4, v255, 10
	s_waitcnt lgkmcnt(1)
	v_mfma_f32_16x16x32_bf16 v[40:43], v[48:51], v[56:59], v[32:35]
	s_nop 2
	ds_read_b128 v[32:35], v109 offset:36928
	ds_read_b64_tr_b16 v[48:49], v104 offset:23616
	ds_read_b128 v[56:59], v108 offset:36928
	s_and_b64 vcc, exec, s[34:35]
	s_waitcnt lgkmcnt(2)
	v_mfma_f32_16x16x32_bf16 v[60:63], v[52:55], v[32:35], v[44:47]
	s_nop 2
	ds_read_b64_tr_b16 v[46:47], v104 offset:23040
	ds_read_b64_tr_b16 v[32:33], v106 offset:32256
	s_waitcnt lgkmcnt(2)
	v_mfma_f32_16x16x32_bf16 v[36:39], v[52:55], v[56:59], v[36:39]
	ds_read_b64_tr_b16 v[34:35], v106 offset:32832
	ds_read_b64_tr_b16 v[50:51], v107 offset:32256
	ds_read_b64_tr_b16 v[52:53], v107 offset:32832
	ds_read_b128 v[54:57], v105 offset:46080
	s_waitcnt lgkmcnt(3)
	v_mfma_f32_16x16x32_bf16 v[32:35], v[46:49], v[32:35], v[28:31]
	s_waitcnt lgkmcnt(1)
	v_mfma_f32_16x16x32_bf16 v[28:31], v[46:49], v[50:53], v[40:43]
	s_nop 2
	ds_read_b128 v[40:43], v109 offset:9216
	ds_read_b128 v[44:47], v108 offset:9216
	ds_read_b128 v[48:51], v105 offset:46144
	s_waitcnt lgkmcnt(1)
	v_mfma_f32_16x16x32_bf16 v[36:39], v[54:57], v[44:47], v[36:39]
	ds_read_b128 v[44:47], v109 offset:9280
	v_mfma_f32_16x16x32_bf16 v[40:43], v[54:57], v[40:43], v[60:63]
	s_waitcnt lgkmcnt(0)
	v_mfma_f32_16x16x32_bf16 v[40:43], v[48:51], v[44:47], v[40:43]
	ds_read_b128 v[44:47], v108 offset:9280
	s_waitcnt lgkmcnt(0)
	v_mfma_f32_16x16x32_bf16 v[36:39], v[48:51], v[44:47], v[36:39]
	v_cvt_pk_bf16_f32 v44, v32, v33
	v_cvt_pk_bf16_f32 v45, v34, v35
	ds_write_b64 v113, v[44:45] offset:55296
	v_cvt_pk_bf16_f32 v44, v28, v29
	v_cvt_pk_bf16_f32 v45, v30, v31
	ds_write_b64 v112, v[44:45] offset:55296
	v_add_u32_e32 v44, s48, v75
	v_lshl_or_b32 v180, v44, 10, v76
	v_cvt_pk_bf16_f32 v40, v40, v41
	v_cvt_pk_bf16_f32 v41, v42, v43
	v_lshl_add_u64 v[42:43], v[180:181], 1, s[92:93]
	global_store_dwordx2 v[42:43], v[40:41], off
	v_add_u32_e32 v40, s48, v77
	v_lshl_or_b32 v180, v40, 10, v76
	v_cvt_pk_bf16_f32 v36, v36, v37
	v_cvt_pk_bf16_f32 v37, v38, v39
	v_lshl_add_u64 v[38:39], v[180:181], 1, s[92:93]
	global_store_dwordx2 v[38:39], v[36:37], off
	v_mov_b32_e32 v36, v68
	s_waitcnt lgkmcnt(0)
	s_barrier
	v_mov_b32_e32 v43, 0
	v_lshrrev_b32_e32 v37, 3, v36
	v_and_or_b32 v40, v37, 7, s70
	v_and_b32_e32 v41, 7, v36
	v_lshlrev_b32_e32 v36, 8, v40
	v_lshlrev_b32_e32 v37, 5, v41
	v_add3_u32 v36, s4, v36, v37
	ds_read_b128 v[44:47], v36
	ds_read_b128 v[36:39], v36 offset:16
	v_mul_lo_u32 v116, v40, s72
	v_lshlrev_b32_e32 v117, 4, v41
	v_lshlrev_b32_e32 v115, 3, v41
	v_add3_u32 v114, 0, v116, v117
	v_mov_b32_e32 v42, 0
	v_mov_b32_e32 v41, 0
	v_mov_b32_e32 v40, 0
	v_mov_b32_e32 v51, 0
	v_mov_b32_e32 v50, 0
	v_mov_b32_e32 v49, 0
	v_mov_b32_e32 v48, 0
	s_waitcnt vmcnt(7)
	ds_write_b128 v114, v[24:27] offset:27648
	s_cbranch_vccnz .LBB0_510
	v_lshl_add_u32 v40, v115, 2, s62
	ds_read_b128 v[48:51], v40
	ds_read_b128 v[40:43], v40 offset:16

.LBB0_525:
	s_andn2_b64 vcc, exec, s[34:35]
	s_mov_b64 s[100:101], s[34:35]
	s_waitcnt lgkmcnt(0)
	s_barrier
	s_cbranch_vccnz .LBB0_535
	v_mov_b32_e32 v170, 0
	v_mov_b32_e32 v172, 0
	s_and_b64 vcc, exec, s[8:9]
	s_cbranch_vccz .Lefb_1
	s_and_b64 vcc, exec, s[30:31]
	s_cbranch_vccz .Lefb_0
	ds_read_b32 v170, v86
.Lefb_0:
	ds_read_b32 v171, v87
.Lefb_1:
	s_and_b64 vcc, exec, s[10:11]
	s_cbranch_vccz .Lefb_2
	ds_read_b32 v172, v88
.Lefb_2:
	s_and_b64 vcc, exec, s[12:13]
	s_cbranch_vccz .Lefb_3
	ds_read_b32 v173, v85 offset:16128
.Lefb_3:
.LBB0_535:
	s_lshl_b32 s35, s40, 6
	s_mov_b64 s[4:5], -1
	s_and_b64 vcc, exec, s[42:43]
	s_cbranch_vccz .LBB0_537
	s_add_i32 s34, s35, 0xffffff00
	s_sub_i32 s36, 0x10ff, s35
	s_and_b64 s[4:5], s[6:7], exec
	s_cselect_b32 s4, s34, s36
	s_add_i32 s34, s4, s76
	s_cbranch_execnz .LBB0_480
	s_branch .LBB0_538

	.amdhsa_kernel _Z4mega6Params
		.amdhsa_group_segment_fixed_size 0
		.amdhsa_private_segment_fixed_size 0
		.amdhsa_kernarg_size 520
		.amdhsa_user_sgpr_count 2
		.amdhsa_user_sgpr_dispatch_ptr 0
		.amdhsa_user_sgpr_queue_ptr 0
		.amdhsa_user_sgpr_kernarg_segment_ptr 1
		.amdhsa_user_sgpr_dispatch_id 0
		.amdhsa_user_sgpr_kernarg_preload_length 0
		.amdhsa_user_sgpr_kernarg_preload_offset 0
		.amdhsa_user_sgpr_private_segment_size 0
		.amdhsa_uses_dynamic_stack 0
		.amdhsa_enable_private_segment 0
		.amdhsa_system_sgpr_workgroup_id_x 1
		.amdhsa_system_sgpr_workgroup_id_y 0
		.amdhsa_system_sgpr_workgroup_id_z 0
		.amdhsa_system_sgpr_workgroup_info 0
		.amdhsa_system_vgpr_workitem_id 2
		.amdhsa_next_free_vgpr 256
		.amdhsa_next_free_sgpr 102
		.amdhsa_accum_offset 256
		.amdhsa_reserve_vcc 1
		.amdhsa_float_round_mode_32 0
		.amdhsa_float_round_mode_16_64 0
		.amdhsa_float_denorm_mode_32 3
		.amdhsa_float_denorm_mode_16_64 3
		.amdhsa_dx10_clamp 1
		.amdhsa_ieee_mode 1
		.amdhsa_fp16_overflow 0
		.amdhsa_tg_split 0
		.amdhsa_exception_fp_ieee_invalid_op 0
		.amdhsa_exception_fp_denorm_src 0
		.amdhsa_exception_fp_ieee_div_zero 0
		.amdhsa_exception_fp_ieee_overflow 0
		.amdhsa_exception_fp_ieee_underflow 0
		.amdhsa_exception_fp_ieee_inexact 0
		.amdhsa_exception_int_div_zero 0
	.end_amdhsa_kernel

amdhsa.kernels:
  - .agpr_count:     0
    .args:
      - .offset:         0
        .size:           264
        .value_kind:     by_value
      - .offset:         264
        .size:           4
        .value_kind:     hidden_block_count_x
      - .offset:         268
        .size:           4
        .value_kind:     hidden_block_count_y
      - .offset:         272
        .size:           4
        .value_kind:     hidden_block_count_z
      - .offset:         276
        .size:           2
        .value_kind:     hidden_group_size_x
      - .offset:         278
        .size:           2
        .value_kind:     hidden_group_size_y
      - .offset:         280
        .size:           2
        .value_kind:     hidden_group_size_z
      - .offset:         282
        .size:           2
        .value_kind:     hidden_remainder_x
      - .offset:         284
        .size:           2
        .value_kind:     hidden_remainder_y
      - .offset:         286
        .size:           2
        .value_kind:     hidden_remainder_z
      - .offset:         304
        .size:           8
        .value_kind:     hidden_global_offset_x
      - .offset:         312
        .size:           8
        .value_kind:     hidden_global_offset_y
      - .offset:         320
        .size:           8
        .value_kind:     hidden_global_offset_z
      - .offset:         328
        .size:           2
        .value_kind:     hidden_grid_dims
      - .offset:         352
        .size:           8
        .value_kind:     hidden_multigrid_sync_arg
      - .offset:         384
        .size:           4
        .value_kind:     hidden_dynamic_lds_size
    .group_segment_fixed_size: 0
    .kernarg_segment_align: 8
    .kernarg_segment_size: 520
    .language:       OpenCL C
    .language_version:
      - 2
      - 0
    .max_flat_workgroup_size: 512
    .name:           _Z4mega6Params
    .private_segment_fixed_size: 0
    .sgpr_count:     108
    .sgpr_spill_count: 36
    .symbol:         _Z4mega6Params.kd
    .uniform_work_group_size: 1
    .uses_dynamic_stack: false
    .vgpr_count:     256
    .vgpr_spill_count: 0
    .wavefront_size: 64
